# write-through (sc0 sc1) stores for the prep-phase weight conversions
# baseline (speedup 1.0000x reference)
.LBB0_71:
	s_or_b64 exec, exec, s[12:13]
	s_mul_hi_i32 s6, s27, 0x5d00
	s_mulk_i32 s27, 0x5d00
	s_ashr_i32 s11, s29, 31
	s_waitcnt vmcnt(0)
	v_cvt_pk_bf16_f32 v96, v9, v11
	v_cvt_pk_bf16_f32 v97, v15, v13
	v_cvt_pk_bf16_f32 v98, v19, v17
	v_cvt_pk_bf16_f32 v99, v23, v21
	s_add_u32 s10, s27, s29
	ds_write_b128 v5, v[96:99]
	v_cvt_pk_bf16_f32 v96, v27, v25
	v_cvt_pk_bf16_f32 v97, v31, v29
	v_cvt_pk_bf16_f32 v98, v35, v33
	v_cvt_pk_bf16_f32 v99, v39, v37
	s_addc_u32 s11, s6, s11
	ds_write_b128 v5, v[96:99] offset:16
	v_cvt_pk_bf16_f32 v99, v55, v54
	v_cvt_pk_bf16_f32 v52, v57, v56
	v_cvt_pk_bf16_f32 v53, v59, v58
	v_cvt_pk_bf16_f32 v54, v61, v60
	v_cvt_pk_bf16_f32 v55, v63, v62
	s_lshl_b64 s[10:11], s[10:11], 12
	ds_write_b128 v5, v[52:55] offset:48
	v_cvt_pk_bf16_f32 v52, v65, v64
	v_cvt_pk_bf16_f32 v53, v67, v66
	v_cvt_pk_bf16_f32 v54, v69, v68
	v_cvt_pk_bf16_f32 v55, v71, v70
	s_add_u32 s6, s42, s10
	ds_write_b128 v5, v[52:55] offset:64
	v_cvt_pk_bf16_f32 v52, v73, v72
	v_cvt_pk_bf16_f32 v53, v75, v74
	v_cvt_pk_bf16_f32 v54, v77, v76
	v_cvt_pk_bf16_f32 v55, v79, v78
	s_addc_u32 s12, s43, s11
	s_lshl_b32 s10, s31, 6
	ds_write_b128 v5, v[52:55] offset:80
	v_cvt_pk_bf16_f32 v52, v81, v80
	v_cvt_pk_bf16_f32 v53, v83, v82
	v_cvt_pk_bf16_f32 v54, v85, v84
	v_cvt_pk_bf16_f32 v55, v87, v86
	s_ashr_i32 s11, s10, 31
	v_cvt_pk_bf16_f32 v96, v43, v41
	v_cvt_pk_bf16_f32 v97, v47, v45
	v_cvt_pk_bf16_f32 v98, v51, v49
	ds_write_b128 v5, v[52:55] offset:96
	v_cvt_pk_bf16_f32 v52, v89, v88
	v_cvt_pk_bf16_f32 v53, v91, v90
	v_cvt_pk_bf16_f32 v54, v93, v92
	v_cvt_pk_bf16_f32 v55, v95, v94
	s_lshl_b64 s[10:11], s[10:11], 1
	ds_write_b128 v5, v[96:99] offset:32
	ds_write_b128 v5, v[52:55] offset:112
	s_add_u32 s10, s6, s10
	s_waitcnt lgkmcnt(0)
	s_addc_u32 s11, s12, s11
	v_mov_b32_e32 v51, v1
	ds_read_b128 v[52:55], v7
	v_lshl_add_u64 v[60:61], s[10:11], 0, v[50:51]
	v_lshlrev_b32_e32 v56, 1, v2
	v_mov_b32_e32 v57, v1
	v_lshl_add_u64 v[62:63], v[60:61], 0, v[56:57]
	ds_read_b128 v[56:59], v7 offset:1152
	s_waitcnt lgkmcnt(1)
	global_store_dwordx4 v[62:63], v[52:55], off sc0 sc1
	s_nop 1
	v_lshlrev_b32_e32 v52, 1, v4
	v_mov_b32_e32 v53, v1
	v_lshl_add_u64 v[52:53], v[60:61], 0, v[52:53]
	s_waitcnt lgkmcnt(0)
	global_store_dwordx4 v[52:53], v[56:59], off sc0 sc1
	ds_read_b128 v[52:55], v7 offset:2304
	s_nop 0
	v_lshlrev_b32_e32 v56, 1, v6
	v_mov_b32_e32 v57, v1
	v_lshl_add_u64 v[62:63], v[60:61], 0, v[56:57]
	ds_read_b128 v[56:59], v7 offset:3456
	s_waitcnt lgkmcnt(1)
	global_store_dwordx4 v[62:63], v[52:55], off sc0 sc1
	s_nop 1
	v_lshlrev_b32_e32 v52, 1, v8
	v_mov_b32_e32 v53, v1
	v_lshl_add_u64 v[52:53], v[60:61], 0, v[52:53]
	s_waitcnt lgkmcnt(0)
	global_store_dwordx4 v[52:53], v[56:59], off sc0 sc1
	ds_read_b128 v[52:55], v7 offset:4608
	s_nop 0
	v_lshlrev_b32_e32 v56, 1, v10
	v_mov_b32_e32 v57, v1
	v_lshl_add_u64 v[62:63], v[60:61], 0, v[56:57]
	ds_read_b128 v[56:59], v7 offset:5760
	s_waitcnt lgkmcnt(1)
	global_store_dwordx4 v[62:63], v[52:55], off sc0 sc1
	s_nop 1
	v_lshlrev_b32_e32 v52, 1, v12
	v_mov_b32_e32 v53, v1
	v_lshl_add_u64 v[52:53], v[60:61], 0, v[52:53]
	s_waitcnt lgkmcnt(0)
	global_store_dwordx4 v[52:53], v[56:59], off sc0 sc1
	ds_read_b128 v[52:55], v7 offset:6912
	s_nop 0
	v_lshlrev_b32_e32 v56, 1, v14
	v_mov_b32_e32 v57, v1
	v_lshl_add_u64 v[62:63], v[60:61], 0, v[56:57]
	ds_read_b128 v[56:59], v7 offset:8064
	s_waitcnt lgkmcnt(1)
	global_store_dwordx4 v[62:63], v[52:55], off sc0 sc1
	s_nop 1
	v_lshlrev_b32_e32 v52, 1, v16
	v_mov_b32_e32 v53, v1
	v_lshl_add_u64 v[52:53], v[60:61], 0, v[52:53]
	s_waitcnt lgkmcnt(0)
	global_store_dwordx4 v[52:53], v[56:59], off sc0 sc1
	s_waitcnt lgkmcnt(0)

.LBB0_73:
	v_readfirstlane_b32 s12, v3
	s_cmpk_gt_i32 s12, 0x54ff
	s_mov_b64 s[10:11], -1
	s_cbranch_scc0 .LBB0_91
	s_cmpk_gt_u32 s12, 0x6cff
	s_cbranch_scc0 .LBB0_88
	s_cmpk_gt_u32 s12, 0x74ff
	s_cbranch_scc0 .LBB0_85
	s_cmpk_gt_u32 s12, 0x76ff
	s_cbranch_scc0 .LBB0_82
	s_cmpk_gt_u32 s12, 0x78ff
	s_cbranch_scc0 .LBB0_79
	s_load_dwordx2 s[10:11], s[0:1], 0x60
	s_add_i32 s6, s12, 0xffff8700
	s_lshr_b32 s6, s6, 2
	s_bfe_u32 s13, s12, 0x10001
	s_and_b32 s27, s12, 1
	s_lshl_b64 s[14:15], s[6:7], 16
	s_waitcnt lgkmcnt(0)
	s_add_u32 s10, s10, s14
	s_addc_u32 s11, s11, s15
	s_lshl_b32 s14, s13, 15
	s_add_u32 s10, s10, s14
	s_addc_u32 s11, s11, 0
	s_lshl_b32 s14, s27, 8
	s_add_u32 s10, s10, s14
	s_addc_u32 s11, s11, 0
	v_lshl_add_u64 v[52:53], s[10:11], 0, v[0:1]
	s_movk_i32 s14, 0x1000
	v_add_co_u32_e32 v54, vcc, s14, v52
	global_load_dword v9, v0, s[10:11]
	global_load_dword v11, v0, s[10:11] offset:512
	global_load_dword v13, v0, s[10:11] offset:1024
	v_addc_co_u32_e32 v55, vcc, 0, v53, vcc
	v_add_co_u32_e32 v56, vcc, s28, v52
	s_nop 1
	v_addc_co_u32_e32 v57, vcc, 0, v53, vcc
	global_load_dword v15, v0, s[10:11] offset:1536
	global_load_dword v17, v0, s[10:11] offset:2048
	global_load_dword v19, v0, s[10:11] offset:2560
	global_load_dword v21, v0, s[10:11] offset:3072
	global_load_dword v23, v0, s[10:11] offset:3584
	global_load_dword v25, v[56:57], off offset:-4096
	global_load_dword v27, v[56:57], off
	global_load_dword v29, v[56:57], off offset:512
	s_movk_i32 s10, 0x3000
	v_add_co_u32_e32 v58, vcc, s10, v52
	s_movk_i32 s10, 0x5000
	s_nop 0
	v_addc_co_u32_e32 v59, vcc, 0, v53, vcc
	v_add_co_u32_e32 v60, vcc, s30, v52
	s_nop 1
	v_addc_co_u32_e32 v61, vcc, 0, v53, vcc
	global_load_dword v31, v[54:55], off offset:512
	global_load_dword v33, v[54:55], off offset:1024
	global_load_dword v35, v[54:55], off offset:1536
	global_load_dword v37, v[54:55], off offset:2048
	global_load_dword v39, v[54:55], off offset:2560
	global_load_dword v41, v[54:55], off offset:3072
	global_load_dword v43, v[54:55], off offset:3584
	global_load_dword v45, v[58:59], off offset:512
	global_load_dword v47, v[56:57], off offset:1024
	global_load_dword v49, v[56:57], off offset:1536
	global_load_dword v51, v[56:57], off offset:2048
	global_load_dword v62, v[56:57], off offset:2560
	global_load_dword v63, v[56:57], off offset:3072
	global_load_dword v64, v[56:57], off offset:3584
	global_load_dword v65, v[60:61], off offset:-4096
	global_load_dword v66, v[60:61], off
	v_add_co_u32_e32 v54, vcc, s10, v52
	s_lshl_b64 s[10:11], s[6:7], 15
	s_nop 0
	v_addc_co_u32_e32 v55, vcc, 0, v53, vcc
	v_add_co_u32_e32 v56, vcc, s34, v52
	v_readlane_b32 s6, v254, 1
	s_nop 0
	v_addc_co_u32_e32 v57, vcc, 0, v53, vcc
	v_add_co_u32_e32 v52, vcc, s35, v52
	global_load_dword v67, v[60:61], off offset:512
	global_load_dword v68, v[60:61], off offset:1024
	global_load_dword v69, v[60:61], off offset:1536
	global_load_dword v70, v[60:61], off offset:2048
	global_load_dword v71, v[60:61], off offset:2560
	global_load_dword v72, v[60:61], off offset:3072
	s_nop 0
	global_load_dword v60, v[60:61], off offset:3584
	s_nop 0
	global_load_dword v61, v[56:57], off offset:-4096
	global_load_dword v73, v[58:59], off offset:1024
	global_load_dword v74, v[58:59], off offset:1536
	global_load_dword v75, v[58:59], off offset:2048
	global_load_dword v76, v[58:59], off offset:2560
	global_load_dword v77, v[58:59], off offset:3072
	s_nop 0
	global_load_dword v58, v[58:59], off offset:3584
	s_nop 0
	global_load_dword v59, v[54:55], off offset:512
	global_load_dword v78, v[54:55], off offset:1024
	global_load_dword v79, v[54:55], off offset:1536
	global_load_dword v80, v[54:55], off offset:2048
	global_load_dword v81, v[54:55], off offset:2560
	global_load_dword v82, v[54:55], off offset:3072
	global_load_dword v83, v[54:55], off offset:3584
	global_load_dword v84, v[56:57], off
	global_load_dword v85, v[56:57], off offset:512
	global_load_dword v86, v[56:57], off offset:1024
	global_load_dword v87, v[56:57], off offset:1536
	global_load_dword v88, v[56:57], off offset:2048
	global_load_dword v89, v[56:57], off offset:2560
	global_load_dword v90, v[56:57], off offset:3072
	s_nop 0
	global_load_dword v56, v[56:57], off offset:3584
	v_addc_co_u32_e32 v53, vcc, 0, v53, vcc
	global_load_dword v57, v[52:53], off
	global_load_dword v91, v[52:53], off offset:512
	global_load_dword v92, v[52:53], off offset:1024
	global_load_dword v93, v[52:53], off offset:1536
	global_load_dword v94, v[52:53], off offset:2048
	global_load_dword v95, v[52:53], off offset:2560
	global_load_dword v96, v[52:53], off offset:3072
	global_load_dword v97, v[52:53], off offset:3584
	s_add_u32 s6, s6, s10
	v_readlane_b32 s10, v254, 3
	s_addc_u32 s10, s10, s11
	s_lshl_b32 s11, s27, 14
	s_add_u32 s6, s6, s11
	s_addc_u32 s11, s10, 0
	s_lshl_b32 s10, s13, 7
	s_add_u32 s10, s6, s10
	s_addc_u32 s11, s11, 0
	s_waitcnt vmcnt(62)
	v_cvt_pk_bf16_f32 v52, v9, v11
	s_waitcnt vmcnt(60)
	v_cvt_pk_bf16_f32 v53, v13, v15
	s_waitcnt vmcnt(58)
	v_cvt_pk_bf16_f32 v54, v17, v19
	v_mov_b32_e32 v19, v1
	s_waitcnt vmcnt(56)
	v_cvt_pk_bf16_f32 v55, v21, v23
	ds_write_b128 v5, v[52:55]
	s_waitcnt vmcnt(52)
	v_cvt_pk_bf16_f32 v52, v25, v31
	s_waitcnt vmcnt(50)
	v_cvt_pk_bf16_f32 v53, v33, v35
	s_waitcnt vmcnt(48)
	v_cvt_pk_bf16_f32 v54, v37, v39
	v_mov_b32_e32 v21, v1
	s_waitcnt vmcnt(46)
	v_cvt_pk_bf16_f32 v55, v41, v43
	ds_write_b128 v5, v[52:55] offset:16
	v_cvt_pk_bf16_f32 v52, v27, v29
	s_waitcnt vmcnt(43)
	v_cvt_pk_bf16_f32 v53, v47, v49
	v_mov_b32_e32 v23, v1
	s_waitcnt vmcnt(41)
	v_cvt_pk_bf16_f32 v54, v51, v62
	v_mov_b32_e32 v51, v1
	s_waitcnt vmcnt(39)
	v_cvt_pk_bf16_f32 v55, v63, v64
	ds_write_b128 v5, v[52:55] offset:32
	s_waitcnt vmcnt(38)
	v_cvt_pk_bf16_f32 v52, v65, v45
	s_waitcnt vmcnt(27)
	v_cvt_pk_bf16_f32 v53, v73, v74
	s_waitcnt vmcnt(25)
	v_cvt_pk_bf16_f32 v54, v75, v76
	s_waitcnt vmcnt(23)
	v_cvt_pk_bf16_f32 v55, v77, v58
	ds_write_b128 v5, v[52:55] offset:48
	v_cvt_pk_bf16_f32 v52, v66, v67
	v_cvt_pk_bf16_f32 v53, v68, v69
	v_cvt_pk_bf16_f32 v54, v70, v71
	v_cvt_pk_bf16_f32 v55, v72, v60
	ds_write_b128 v5, v[52:55] offset:64
	s_waitcnt vmcnt(22)
	v_cvt_pk_bf16_f32 v52, v61, v59
	s_waitcnt vmcnt(20)
	v_cvt_pk_bf16_f32 v53, v78, v79
	s_waitcnt vmcnt(18)
	v_cvt_pk_bf16_f32 v54, v80, v81
	s_waitcnt vmcnt(16)
	v_cvt_pk_bf16_f32 v55, v82, v83
	ds_write_b128 v5, v[52:55] offset:80
	s_waitcnt vmcnt(14)
	v_cvt_pk_bf16_f32 v52, v84, v85
	s_waitcnt vmcnt(12)
	v_cvt_pk_bf16_f32 v53, v86, v87
	s_waitcnt vmcnt(10)
	v_cvt_pk_bf16_f32 v54, v88, v89
	s_waitcnt vmcnt(8)
	v_cvt_pk_bf16_f32 v55, v90, v56
	ds_write_b128 v5, v[52:55] offset:96
	s_waitcnt vmcnt(6)
	v_cvt_pk_bf16_f32 v52, v57, v91
	s_waitcnt vmcnt(4)
	v_cvt_pk_bf16_f32 v53, v92, v93
	s_waitcnt vmcnt(2)
	v_cvt_pk_bf16_f32 v54, v94, v95
	s_waitcnt vmcnt(0)
	v_cvt_pk_bf16_f32 v55, v96, v97
	ds_write_b128 v5, v[52:55] offset:112
	s_waitcnt lgkmcnt(0)
	ds_read_b128 v[52:55], v7
	ds_read_b128 v[56:59], v7 offset:1152
	v_lshl_add_u64 v[60:61], s[10:11], 0, v[50:51]
	v_lshl_add_u64 v[62:63], v[60:61], 0, v[18:19]
	v_mov_b32_e32 v25, v1
	s_waitcnt lgkmcnt(1)
	global_store_dwordx4 v[62:63], v[52:55], off sc0 sc1
	v_lshl_add_u64 v[62:63], v[60:61], 0, v[20:21]
	ds_read_b128 v[52:55], v7 offset:2304
	s_waitcnt lgkmcnt(1)
	global_store_dwordx4 v[62:63], v[56:59], off sc0 sc1
	ds_read_b128 v[56:59], v7 offset:3456
	v_lshl_add_u64 v[62:63], v[60:61], 0, v[22:23]
	v_mov_b32_e32 v27, v1
	s_waitcnt lgkmcnt(1)
	global_store_dwordx4 v[62:63], v[52:55], off sc0 sc1
	v_lshl_add_u64 v[62:63], v[60:61], 0, v[24:25]
	ds_read_b128 v[52:55], v7 offset:4608
	s_waitcnt lgkmcnt(1)
	global_store_dwordx4 v[62:63], v[56:59], off sc0 sc1
	ds_read_b128 v[56:59], v7 offset:5760
	v_lshl_add_u64 v[62:63], v[60:61], 0, v[26:27]
	v_mov_b32_e32 v29, v1
	s_waitcnt lgkmcnt(1)
	global_store_dwordx4 v[62:63], v[52:55], off sc0 sc1
	v_lshl_add_u64 v[62:63], v[60:61], 0, v[28:29]
	ds_read_b128 v[52:55], v7 offset:6912
	s_waitcnt lgkmcnt(1)
	global_store_dwordx4 v[62:63], v[56:59], off sc0 sc1
	ds_read_b128 v[56:59], v7 offset:8064
	v_mov_b32_e32 v31, v1
	v_lshl_add_u64 v[62:63], v[60:61], 0, v[30:31]
	v_mov_b32_e32 v33, v1
	s_waitcnt lgkmcnt(1)
	global_store_dwordx4 v[62:63], v[52:55], off sc0 sc1
	s_mov_b64 s[10:11], 0
	s_nop 0
	v_lshl_add_u64 v[52:53], v[60:61], 0, v[32:33]
	s_waitcnt lgkmcnt(0)
	global_store_dwordx4 v[52:53], v[56:59], off sc0 sc1
	s_waitcnt lgkmcnt(0)
.LBB0_79:
	s_andn2_b64 vcc, exec, s[10:11]
	s_cbranch_vccnz .LBB0_81
	s_load_dwordx2 s[10:11], s[0:1], 0x58
	s_add_i32 s6, s12, 0xffff8900
	s_lshr_b32 s6, s6, 7
	s_lshl_b64 s[14:15], s[6:7], 21
	s_waitcnt lgkmcnt(0)
	s_add_u32 s10, s10, s14
	s_addc_u32 s11, s11, s15
	s_lshl_b32 s13, s12, 5
	s_lshl_b32 s14, s12, 12
	s_and_b32 s13, s13, 0x7c0
	s_and_b32 s14, s14, 0x40000
	s_lshl_b32 s15, s14, 2
	s_lshl_b32 s27, s13, 9
	s_or_b32 s15, s27, s15
	s_add_u32 s10, s10, s15
	s_addc_u32 s11, s11, 0
	s_lshl_b32 s15, s12, 6
	s_and_b32 s15, s15, 64
	s_lshl_b32 s27, s15, 2
	s_add_u32 s10, s10, s27
	s_addc_u32 s11, s11, 0
	v_lshl_add_u64 v[52:53], s[10:11], 0, v[0:1]
	s_movk_i32 s27, 0x1000
	v_add_co_u32_e32 v54, vcc, s27, v52
	global_load_dword v9, v0, s[10:11]
	global_load_dword v11, v0, s[10:11] offset:512
	global_load_dword v13, v0, s[10:11] offset:1024
	v_addc_co_u32_e32 v55, vcc, 0, v53, vcc
	v_add_co_u32_e32 v56, vcc, s28, v52
	s_nop 1
	v_addc_co_u32_e32 v57, vcc, 0, v53, vcc
	global_load_dword v15, v0, s[10:11] offset:1536
	global_load_dword v17, v0, s[10:11] offset:2048
	global_load_dword v19, v0, s[10:11] offset:2560
	global_load_dword v21, v0, s[10:11] offset:3072
	global_load_dword v23, v0, s[10:11] offset:3584
	global_load_dword v25, v[56:57], off offset:-4096
	global_load_dword v27, v[56:57], off
	global_load_dword v29, v[56:57], off offset:512
	s_movk_i32 s10, 0x3000
	v_add_co_u32_e32 v58, vcc, s10, v52
	s_movk_i32 s10, 0x5000
	s_nop 0
	v_addc_co_u32_e32 v59, vcc, 0, v53, vcc
	v_add_co_u32_e32 v60, vcc, s30, v52
	s_nop 1
	v_addc_co_u32_e32 v61, vcc, 0, v53, vcc
	global_load_dword v31, v[54:55], off offset:512
	global_load_dword v33, v[54:55], off offset:1024
	global_load_dword v35, v[54:55], off offset:1536
	global_load_dword v37, v[54:55], off offset:2048
	global_load_dword v39, v[54:55], off offset:2560
	global_load_dword v41, v[54:55], off offset:3072
	global_load_dword v43, v[54:55], off offset:3584
	global_load_dword v45, v[58:59], off offset:512
	global_load_dword v47, v[56:57], off offset:1024
	global_load_dword v49, v[56:57], off offset:1536
	global_load_dword v51, v[56:57], off offset:2048
	global_load_dword v62, v[56:57], off offset:2560
	global_load_dword v63, v[56:57], off offset:3072
	global_load_dword v64, v[56:57], off offset:3584
	global_load_dword v65, v[60:61], off offset:-4096
	global_load_dword v66, v[60:61], off
	v_add_co_u32_e32 v54, vcc, s10, v52
	s_lshl_b64 s[10:11], s[6:7], 20
	s_nop 0
	v_addc_co_u32_e32 v55, vcc, 0, v53, vcc
	v_add_co_u32_e32 v56, vcc, s34, v52
	v_readlane_b32 s6, v254, 4
	s_nop 0
	v_addc_co_u32_e32 v57, vcc, 0, v53, vcc
	v_add_co_u32_e32 v52, vcc, s35, v52
	global_load_dword v67, v[60:61], off offset:512
	global_load_dword v68, v[60:61], off offset:1024
	global_load_dword v69, v[60:61], off offset:1536
	global_load_dword v70, v[60:61], off offset:2048
	global_load_dword v71, v[60:61], off offset:2560
	global_load_dword v72, v[60:61], off offset:3072
	s_nop 0
	global_load_dword v60, v[60:61], off offset:3584
	s_nop 0
	global_load_dword v61, v[56:57], off offset:-4096
	global_load_dword v73, v[58:59], off offset:1024
	global_load_dword v74, v[58:59], off offset:1536
	global_load_dword v75, v[58:59], off offset:2048
	global_load_dword v76, v[58:59], off offset:2560
	global_load_dword v77, v[58:59], off offset:3072
	s_nop 0
	global_load_dword v58, v[58:59], off offset:3584
	s_nop 0
	global_load_dword v59, v[54:55], off offset:512
	global_load_dword v78, v[54:55], off offset:1024
	global_load_dword v79, v[54:55], off offset:1536
	global_load_dword v80, v[54:55], off offset:2048
	global_load_dword v81, v[54:55], off offset:2560
	global_load_dword v82, v[54:55], off offset:3072
	global_load_dword v83, v[54:55], off offset:3584
	global_load_dword v84, v[56:57], off
	global_load_dword v85, v[56:57], off offset:512
	global_load_dword v86, v[56:57], off offset:1024
	global_load_dword v87, v[56:57], off offset:1536
	global_load_dword v88, v[56:57], off offset:2048
	global_load_dword v89, v[56:57], off offset:2560
	global_load_dword v90, v[56:57], off offset:3072
	s_nop 0
	global_load_dword v56, v[56:57], off offset:3584
	v_addc_co_u32_e32 v53, vcc, 0, v53, vcc
	global_load_dword v57, v[52:53], off
	global_load_dword v91, v[52:53], off offset:512
	global_load_dword v92, v[52:53], off offset:1024
	global_load_dword v93, v[52:53], off offset:1536
	global_load_dword v94, v[52:53], off offset:2048
	global_load_dword v95, v[52:53], off offset:2560
	global_load_dword v96, v[52:53], off offset:3072
	global_load_dword v97, v[52:53], off offset:3584
	s_add_u32 s6, s6, s10
	v_readlane_b32 s10, v254, 5
	s_addc_u32 s10, s10, s11
	s_lshl_b32 s11, s14, 1
	s_lshl_b32 s14, s15, 12
	s_or_b32 s11, s14, s11
	s_add_u32 s6, s6, s11
	s_addc_u32 s11, s10, 0
	s_lshl_b32 s10, s13, 1
	s_add_u32 s10, s6, s10
	s_addc_u32 s11, s11, 0
	s_waitcnt vmcnt(62)
	v_cvt_pk_bf16_f32 v52, v9, v11
	s_waitcnt vmcnt(60)
	v_cvt_pk_bf16_f32 v53, v13, v15
	s_waitcnt vmcnt(58)
	v_cvt_pk_bf16_f32 v54, v17, v19
	s_waitcnt vmcnt(56)
	v_cvt_pk_bf16_f32 v55, v21, v23
	ds_write_b128 v5, v[52:55]
	s_waitcnt vmcnt(52)
	v_cvt_pk_bf16_f32 v52, v25, v31
	s_waitcnt vmcnt(50)
	v_cvt_pk_bf16_f32 v53, v33, v35
	s_waitcnt vmcnt(48)
	v_cvt_pk_bf16_f32 v54, v37, v39
	s_waitcnt vmcnt(46)
	v_cvt_pk_bf16_f32 v55, v41, v43
	ds_write_b128 v5, v[52:55] offset:16
	v_cvt_pk_bf16_f32 v52, v27, v29
	s_waitcnt vmcnt(43)
	v_cvt_pk_bf16_f32 v53, v47, v49
	s_waitcnt vmcnt(41)
	v_cvt_pk_bf16_f32 v54, v51, v62
	v_mov_b32_e32 v51, v1
	s_waitcnt vmcnt(39)
	v_cvt_pk_bf16_f32 v55, v63, v64
	ds_write_b128 v5, v[52:55] offset:32
	s_waitcnt vmcnt(38)
	v_cvt_pk_bf16_f32 v52, v65, v45
	s_waitcnt vmcnt(27)
	v_cvt_pk_bf16_f32 v53, v73, v74
	s_waitcnt vmcnt(25)
	v_cvt_pk_bf16_f32 v54, v75, v76
	s_waitcnt vmcnt(23)
	v_cvt_pk_bf16_f32 v55, v77, v58
	ds_write_b128 v5, v[52:55] offset:48
	v_cvt_pk_bf16_f32 v52, v66, v67
	v_cvt_pk_bf16_f32 v53, v68, v69
	v_cvt_pk_bf16_f32 v54, v70, v71
	v_cvt_pk_bf16_f32 v55, v72, v60
	ds_write_b128 v5, v[52:55] offset:64
	s_waitcnt vmcnt(22)
	v_cvt_pk_bf16_f32 v52, v61, v59
	s_waitcnt vmcnt(20)
	v_cvt_pk_bf16_f32 v53, v78, v79
	s_waitcnt vmcnt(18)
	v_cvt_pk_bf16_f32 v54, v80, v81
	s_waitcnt vmcnt(16)
	v_cvt_pk_bf16_f32 v55, v82, v83
	ds_write_b128 v5, v[52:55] offset:80
	s_waitcnt vmcnt(14)
	v_cvt_pk_bf16_f32 v52, v84, v85
	s_waitcnt vmcnt(12)
	v_cvt_pk_bf16_f32 v53, v86, v87
	s_waitcnt vmcnt(10)
	v_cvt_pk_bf16_f32 v54, v88, v89
	s_waitcnt vmcnt(8)
	v_cvt_pk_bf16_f32 v55, v90, v56
	ds_write_b128 v5, v[52:55] offset:96
	s_waitcnt vmcnt(6)
	v_cvt_pk_bf16_f32 v52, v57, v91
	s_waitcnt vmcnt(4)
	v_cvt_pk_bf16_f32 v53, v92, v93
	s_waitcnt vmcnt(2)
	v_cvt_pk_bf16_f32 v54, v94, v95
	s_waitcnt vmcnt(0)
	v_cvt_pk_bf16_f32 v55, v96, v97
	ds_write_b128 v5, v[52:55] offset:112
	s_waitcnt lgkmcnt(0)
	ds_read_b128 v[52:55], v7
	v_lshl_add_u64 v[60:61], s[10:11], 0, v[50:51]
	v_lshlrev_b32_e32 v56, 1, v2
	v_mov_b32_e32 v57, v1
	v_lshl_add_u64 v[62:63], v[60:61], 0, v[56:57]
	ds_read_b128 v[56:59], v7 offset:1152
	s_waitcnt lgkmcnt(1)
	global_store_dwordx4 v[62:63], v[52:55], off sc0 sc1
	s_nop 1
	v_lshlrev_b32_e32 v52, 1, v4
	v_mov_b32_e32 v53, v1
	v_lshl_add_u64 v[52:53], v[60:61], 0, v[52:53]
	s_waitcnt lgkmcnt(0)
	global_store_dwordx4 v[52:53], v[56:59], off sc0 sc1
	ds_read_b128 v[52:55], v7 offset:2304
	s_nop 0
	v_lshlrev_b32_e32 v56, 1, v6
	v_mov_b32_e32 v57, v1
	v_lshl_add_u64 v[62:63], v[60:61], 0, v[56:57]
	ds_read_b128 v[56:59], v7 offset:3456
	s_waitcnt lgkmcnt(1)
	global_store_dwordx4 v[62:63], v[52:55], off sc0 sc1
	s_nop 1
	v_lshlrev_b32_e32 v52, 1, v8
	v_mov_b32_e32 v53, v1
	v_lshl_add_u64 v[52:53], v[60:61], 0, v[52:53]
	s_waitcnt lgkmcnt(0)
	global_store_dwordx4 v[52:53], v[56:59], off sc0 sc1
	ds_read_b128 v[52:55], v7 offset:4608
	s_nop 0
	v_lshlrev_b32_e32 v56, 1, v10
	v_mov_b32_e32 v57, v1
	v_lshl_add_u64 v[62:63], v[60:61], 0, v[56:57]
	ds_read_b128 v[56:59], v7 offset:5760
	s_waitcnt lgkmcnt(1)
	global_store_dwordx4 v[62:63], v[52:55], off sc0 sc1
	s_nop 1
	v_lshlrev_b32_e32 v52, 1, v12
	v_mov_b32_e32 v53, v1
	v_lshl_add_u64 v[52:53], v[60:61], 0, v[52:53]
	s_waitcnt lgkmcnt(0)
	global_store_dwordx4 v[52:53], v[56:59], off sc0 sc1
	ds_read_b128 v[52:55], v7 offset:6912
	s_nop 0
	v_lshlrev_b32_e32 v56, 1, v14
	v_mov_b32_e32 v57, v1
	v_lshl_add_u64 v[62:63], v[60:61], 0, v[56:57]
	ds_read_b128 v[56:59], v7 offset:8064
	s_waitcnt lgkmcnt(1)
	global_store_dwordx4 v[62:63], v[52:55], off sc0 sc1
	s_nop 1
	v_lshlrev_b32_e32 v52, 1, v16
	v_mov_b32_e32 v53, v1
	v_lshl_add_u64 v[52:53], v[60:61], 0, v[52:53]
	s_waitcnt lgkmcnt(0)
	global_store_dwordx4 v[52:53], v[56:59], off sc0 sc1
	s_waitcnt lgkmcnt(0)

.LBB0_82:
	s_andn2_b64 vcc, exec, s[10:11]
	s_cbranch_vccnz .LBB0_84
	s_load_dwordx2 s[14:15], s[0:1], 0x70
	s_add_i32 s6, s12, 0xffff8b00
	s_lshr_b32 s6, s6, 6
	s_bfe_u32 s10, s12, 0x30003
	s_and_b32 s11, s12, 7
	s_lshl_b64 vcc, s[6:7], 20
	s_waitcnt lgkmcnt(0)
	s_add_u32 s13, s14, vcc_lo
	s_addc_u32 s14, s15, vcc_hi
	s_lshl_b32 s15, s10, 17
	s_add_u32 s13, s13, s15
	s_addc_u32 s15, s14, 0
	s_lshl_b32 s14, s11, 8
	s_add_u32 s14, s13, s14
	s_addc_u32 s15, s15, 0
	v_lshl_add_u64 v[52:53], s[14:15], 0, v[0:1]
	s_movk_i32 s13, 0x1000
	v_add_co_u32_e32 v54, vcc, s13, v52
	s_movk_i32 s13, 0x3000
	s_nop 0
	v_addc_co_u32_e32 v55, vcc, 0, v53, vcc
	v_add_co_u32_e32 v56, vcc, s28, v52
	s_nop 1
	v_addc_co_u32_e32 v57, vcc, 0, v53, vcc
	v_add_co_u32_e32 v58, vcc, s13, v52
	s_movk_i32 s13, 0x5000
	s_nop 0
	v_addc_co_u32_e32 v59, vcc, 0, v53, vcc
	v_add_co_u32_e32 v60, vcc, s30, v52
	s_nop 1
	v_addc_co_u32_e32 v61, vcc, 0, v53, vcc
	global_load_dword v9, v0, s[14:15]
	global_load_dword v11, v0, s[14:15] offset:2048
	global_load_dword v13, v[56:57], off offset:-4096
	global_load_dword v15, v[56:57], off
	global_load_dword v17, v[56:57], off offset:2048
	global_load_dword v19, v[60:61], off offset:-4096
	global_load_dword v21, v[60:61], off
	v_add_co_u32_e32 v56, vcc, s13, v52
	s_mov_b32 s13, 0x9000
	s_nop 0
	v_addc_co_u32_e32 v57, vcc, 0, v53, vcc
	v_add_co_u32_e32 v62, vcc, s34, v52
	s_lshl_b64 s[14:15], s[6:7], 19
	s_nop 0
	v_addc_co_u32_e32 v63, vcc, 0, v53, vcc
	v_add_co_u32_e32 v64, vcc, s35, v52
	s_add_u32 s6, s21, s14
	s_nop 0
	v_addc_co_u32_e32 v65, vcc, 0, v53, vcc
	v_add_co_u32_e32 v66, vcc, s37, v52
	s_nop 1
	v_addc_co_u32_e32 v67, vcc, 0, v53, vcc
	v_add_co_u32_e32 v68, vcc, s13, v52
	s_mov_b32 s13, 0xb000
	s_nop 0
	v_addc_co_u32_e32 v69, vcc, 0, v53, vcc
	v_add_co_u32_e32 v70, vcc, s38, v52
	s_nop 1
	v_addc_co_u32_e32 v71, vcc, 0, v53, vcc
	global_load_dword v23, v[60:61], off offset:2048
	global_load_dword v25, v[62:63], off offset:-4096
	global_load_dword v27, v[62:63], off
	global_load_dword v29, v[62:63], off offset:2048
	global_load_dword v31, v[66:67], off offset:-4096
	global_load_dword v33, v[66:67], off
	global_load_dword v35, v[66:67], off offset:2048
	global_load_dword v37, v[70:71], off offset:-4096
	v_add_co_u32_e32 v60, vcc, s13, v52
	s_mov_b32 s13, 0xd000
	s_nop 0
	v_addc_co_u32_e32 v61, vcc, 0, v53, vcc
	v_add_co_u32_e32 v62, vcc, s39, v52
	s_nop 1
	v_addc_co_u32_e32 v63, vcc, 0, v53, vcc
	v_add_co_u32_e32 v66, vcc, s13, v52
	s_mov_b32 s13, 0xf000
	s_nop 0
	v_addc_co_u32_e32 v67, vcc, 0, v53, vcc
	v_add_co_u32_e32 v72, vcc, s40, v52
	s_nop 1
	v_addc_co_u32_e32 v73, vcc, 0, v53, vcc
	global_load_dword v39, v[70:71], off
	global_load_dword v41, v[70:71], off offset:2048
	global_load_dword v43, v[62:63], off offset:-4096
	global_load_dword v45, v[62:63], off
	global_load_dword v47, v[62:63], off offset:2048
	global_load_dword v49, v[72:73], off offset:-4096
	global_load_dword v51, v[72:73], off
	s_nop 0
	global_load_dword v72, v[72:73], off offset:2048
	v_add_co_u32_e32 v62, vcc, s13, v52
	s_mov_b32 s13, 0x11000
	s_nop 0
	v_addc_co_u32_e32 v63, vcc, 0, v53, vcc
	v_add_co_u32_e32 v70, vcc, s41, v52
	global_load_dword v73, v[54:55], off offset:2048
	global_load_dword v74, v[58:59], off offset:2048
	global_load_dword v75, v[56:57], off offset:2048
	global_load_dword v76, v[64:65], off offset:2048
	global_load_dword v77, v[68:69], off offset:2048
	global_load_dword v78, v[60:61], off offset:2048
	global_load_dword v79, v[66:67], off offset:2048
	global_load_dword v80, v[62:63], off offset:2048
	v_addc_co_u32_e32 v71, vcc, 0, v53, vcc
	v_add_co_u32_e32 v54, vcc, s13, v52
	s_mov_b32 s13, 0x13000
	s_nop 0
	v_addc_co_u32_e32 v55, vcc, 0, v53, vcc
	v_add_co_u32_e32 v56, vcc, s44, v52
	s_nop 1
	v_addc_co_u32_e32 v57, vcc, 0, v53, vcc
	v_add_co_u32_e32 v58, vcc, s13, v52
	s_mov_b32 s13, 0x15000
	s_nop 0
	v_addc_co_u32_e32 v59, vcc, 0, v53, vcc
	v_add_co_u32_e32 v60, vcc, s45, v52
	s_nop 1
	v_addc_co_u32_e32 v61, vcc, 0, v53, vcc
	global_load_dword v81, v[70:71], off offset:-4096
	global_load_dword v82, v[70:71], off
	global_load_dword v83, v[70:71], off offset:2048
	global_load_dword v84, v[56:57], off offset:-4096
	global_load_dword v85, v[56:57], off
	global_load_dword v86, v[56:57], off offset:2048
	global_load_dword v87, v[60:61], off offset:-4096
	global_load_dword v88, v[60:61], off
	v_add_co_u32_e32 v56, vcc, s13, v52
	s_mov_b32 s13, 0x17000
	s_nop 0
	v_addc_co_u32_e32 v57, vcc, 0, v53, vcc
	v_add_co_u32_e32 v62, vcc, s46, v52
	s_nop 1
	v_addc_co_u32_e32 v63, vcc, 0, v53, vcc
	v_add_co_u32_e32 v64, vcc, s13, v52
	s_mov_b32 s13, 0x19000
	s_nop 0
	v_addc_co_u32_e32 v65, vcc, 0, v53, vcc
	v_add_co_u32_e32 v66, vcc, s47, v52
	s_nop 1
	v_addc_co_u32_e32 v67, vcc, 0, v53, vcc
	v_add_co_u32_e32 v68, vcc, s13, v52
	s_mov_b32 s13, 0x1b000
	s_nop 0
	v_addc_co_u32_e32 v69, vcc, 0, v53, vcc
	v_add_co_u32_e32 v70, vcc, s48, v52
	s_nop 1
	v_addc_co_u32_e32 v71, vcc, 0, v53, vcc
	global_load_dword v89, v[60:61], off offset:2048
	global_load_dword v90, v[62:63], off offset:-4096
	global_load_dword v91, v[62:63], off
	global_load_dword v92, v[62:63], off offset:2048
	global_load_dword v93, v[66:67], off offset:-4096
	global_load_dword v94, v[66:67], off
	s_nop 0
	global_load_dword v66, v[66:67], off offset:2048
	s_nop 0
	global_load_dword v67, v[70:71], off offset:-4096
	v_add_co_u32_e32 v60, vcc, s13, v52
	s_mov_b32 s13, 0x1d000
	s_nop 0
	v_addc_co_u32_e32 v61, vcc, 0, v53, vcc
	v_add_co_u32_e32 v62, vcc, s49, v52
	global_load_dword v95, v[54:55], off offset:2048
	s_nop 0
	global_load_dword v58, v[58:59], off offset:2048
	s_nop 0
	global_load_dword v59, v[56:57], off offset:2048
	s_nop 0
	global_load_dword v64, v[64:65], off offset:2048
	s_nop 0
	global_load_dword v65, v[68:69], off offset:2048
	s_nop 0
	global_load_dword v60, v[60:61], off offset:2048
	v_addc_co_u32_e32 v63, vcc, 0, v53, vcc
	v_add_co_u32_e32 v54, vcc, s13, v52
	s_mov_b32 s13, 0x1f000
	s_nop 0
	v_addc_co_u32_e32 v55, vcc, 0, v53, vcc
	v_add_co_u32_e32 v56, vcc, s51, v52
	s_nop 1
	v_addc_co_u32_e32 v57, vcc, 0, v53, vcc
	v_add_co_u32_e32 v52, vcc, s13, v52
	global_load_dword v61, v[70:71], off
	global_load_dword v68, v[70:71], off offset:2048
	global_load_dword v69, v[62:63], off offset:-4096
	s_nop 0
	global_load_dword v70, v[62:63], off
	s_nop 0
	global_load_dword v62, v[62:63], off offset:2048
	s_nop 0
	global_load_dword v63, v[56:57], off offset:-4096
	global_load_dword v71, v[56:57], off
	s_nop 0
	global_load_dword v56, v[56:57], off offset:2048
	v_addc_co_u32_e32 v53, vcc, 0, v53, vcc
	global_load_dword v57, v[54:55], off offset:2048
	global_load_dword v96, v[52:53], off
	global_load_dword v97, v[52:53], off offset:2048
	s_waitcnt vmcnt(62)
	v_cvt_pk_bf16_f32 v52, v9, v11
	s_waitcnt vmcnt(40)
	v_cvt_pk_bf16_f32 v53, v13, v73
	v_cvt_pk_bf16_f32 v54, v15, v17
	s_waitcnt vmcnt(39)
	v_cvt_pk_bf16_f32 v55, v19, v74
	ds_write_b128 v5, v[52:55]
	v_cvt_pk_bf16_f32 v52, v21, v23
	s_waitcnt vmcnt(38)
	v_cvt_pk_bf16_f32 v53, v25, v75
	v_cvt_pk_bf16_f32 v54, v27, v29
	s_waitcnt vmcnt(37)
	v_cvt_pk_bf16_f32 v55, v31, v76
	ds_write_b128 v5, v[52:55] offset:16
	v_cvt_pk_bf16_f32 v52, v33, v35
	s_waitcnt vmcnt(36)
	v_cvt_pk_bf16_f32 v53, v37, v77
	v_cvt_pk_bf16_f32 v54, v39, v41
	s_waitcnt vmcnt(35)
	v_cvt_pk_bf16_f32 v55, v43, v78
	ds_write_b128 v5, v[52:55] offset:32
	v_cvt_pk_bf16_f32 v52, v45, v47
	s_waitcnt vmcnt(34)
	v_cvt_pk_bf16_f32 v53, v49, v79
	v_cvt_pk_bf16_f32 v54, v51, v72
	s_waitcnt vmcnt(32)
	v_cvt_pk_bf16_f32 v55, v81, v80
	ds_write_b128 v5, v[52:55] offset:48
	s_waitcnt vmcnt(30)
	v_cvt_pk_bf16_f32 v52, v82, v83
	s_waitcnt vmcnt(27)
	v_cvt_pk_bf16_f32 v54, v85, v86
	s_addc_u32 s13, s22, s15
	s_lshl_b32 s11, s11, 16
	s_add_u32 s6, s6, s11
	s_addc_u32 s11, s13, 0
	s_lshl_b32 s10, s10, 7
	s_add_u32 s10, s6, s10
	s_addc_u32 s11, s11, 0
	v_mov_b32_e32 v51, v1
	v_mov_b32_e32 v35, v1
	v_mov_b32_e32 v37, v1
	v_mov_b32_e32 v39, v1
	v_mov_b32_e32 v41, v1
	v_mov_b32_e32 v43, v1
	v_mov_b32_e32 v45, v1
	v_mov_b32_e32 v47, v1
	v_mov_b32_e32 v49, v1
	s_waitcnt vmcnt(16)
	v_cvt_pk_bf16_f32 v53, v84, v95
	s_waitcnt vmcnt(15)
	v_cvt_pk_bf16_f32 v55, v87, v58
	ds_write_b128 v5, v[52:55] offset:64
	v_cvt_pk_bf16_f32 v52, v88, v89
	s_waitcnt vmcnt(14)
	v_cvt_pk_bf16_f32 v53, v90, v59
	v_cvt_pk_bf16_f32 v54, v91, v92
	s_waitcnt vmcnt(13)
	v_cvt_pk_bf16_f32 v55, v93, v64
	ds_write_b128 v5, v[52:55] offset:80
	v_cvt_pk_bf16_f32 v52, v94, v66
	s_waitcnt vmcnt(12)
	v_cvt_pk_bf16_f32 v53, v67, v65
	s_waitcnt vmcnt(9)
	v_cvt_pk_bf16_f32 v54, v61, v68
	s_waitcnt vmcnt(8)
	v_cvt_pk_bf16_f32 v55, v69, v60
	ds_write_b128 v5, v[52:55] offset:96
	s_waitcnt vmcnt(6)
	v_cvt_pk_bf16_f32 v52, v70, v62
	v_lshl_add_u64 v[60:61], s[10:11], 0, v[50:51]
	s_waitcnt vmcnt(3)
	v_cvt_pk_bf16_f32 v54, v71, v56
	s_waitcnt vmcnt(2)
	v_cvt_pk_bf16_f32 v53, v63, v57
	v_lshl_add_u64 v[62:63], v[60:61], 0, v[34:35]
	s_waitcnt vmcnt(0)
	v_cvt_pk_bf16_f32 v55, v96, v97
	ds_write_b128 v5, v[52:55] offset:112
	s_waitcnt lgkmcnt(0)
	ds_read_b128 v[52:55], v7
	ds_read_b128 v[56:59], v7 offset:1152
	s_waitcnt lgkmcnt(1)
	global_store_dwordx4 v[62:63], v[52:55], off sc0 sc1
	v_lshl_add_u64 v[62:63], v[60:61], 0, v[36:37]
	ds_read_b128 v[52:55], v7 offset:2304
	s_waitcnt lgkmcnt(1)
	global_store_dwordx4 v[62:63], v[56:59], off sc0 sc1
	ds_read_b128 v[56:59], v7 offset:3456
	v_lshl_add_u64 v[62:63], v[60:61], 0, v[38:39]
	s_waitcnt lgkmcnt(1)
	global_store_dwordx4 v[62:63], v[52:55], off sc0 sc1
	v_lshl_add_u64 v[62:63], v[60:61], 0, v[40:41]
	ds_read_b128 v[52:55], v7 offset:4608
	s_waitcnt lgkmcnt(1)
	global_store_dwordx4 v[62:63], v[56:59], off sc0 sc1
	ds_read_b128 v[56:59], v7 offset:5760
	v_lshl_add_u64 v[62:63], v[60:61], 0, v[42:43]
	s_waitcnt lgkmcnt(1)
	global_store_dwordx4 v[62:63], v[52:55], off sc0 sc1
	v_lshl_add_u64 v[62:63], v[60:61], 0, v[44:45]
	ds_read_b128 v[52:55], v7 offset:6912
	s_waitcnt lgkmcnt(1)
	global_store_dwordx4 v[62:63], v[56:59], off sc0 sc1
	ds_read_b128 v[56:59], v7 offset:8064
	v_lshl_add_u64 v[62:63], v[60:61], 0, v[46:47]
	s_waitcnt lgkmcnt(1)
	global_store_dwordx4 v[62:63], v[52:55], off sc0 sc1
	s_nop 1
	v_lshl_add_u64 v[52:53], v[60:61], 0, v[48:49]
	s_waitcnt lgkmcnt(0)
	global_store_dwordx4 v[52:53], v[56:59], off sc0 sc1
	s_waitcnt lgkmcnt(0)

.LBB0_85:
	s_andn2_b64 vcc, exec, s[10:11]
	s_cbranch_vccnz .LBB0_87
	s_load_dwordx2 s[14:15], s[0:1], 0x88
	s_add_i32 s10, s12, 0xffff9300
	s_lshr_b32 s6, s10, 10
	s_bfe_u32 s10, s10, 0x50005
	s_and_b32 s11, s12, 31
	s_lshl_b64 vcc, s[6:7], 24
	s_waitcnt lgkmcnt(0)
	s_add_u32 s13, s14, vcc_lo
	s_addc_u32 s14, s15, vcc_hi
	s_lshl_b32 s15, s10, 19
	s_add_u32 s13, s13, s15
	s_addc_u32 s15, s14, 0
	s_lshl_b32 s14, s11, 8
	s_add_u32 s14, s13, s14
	s_addc_u32 s15, s15, 0
	v_lshl_add_u64 v[52:53], s[14:15], 0, v[0:1]
	v_add_co_u32_e32 v54, vcc, s28, v52
	global_load_dword v9, v0, s[14:15]
	s_nop 0
	v_addc_co_u32_e32 v55, vcc, 0, v53, vcc
	v_add_co_u32_e32 v56, vcc, s30, v52
	s_lshl_b64 s[14:15], s[6:7], 23
	s_nop 0
	v_addc_co_u32_e32 v57, vcc, 0, v53, vcc
	v_add_co_u32_e32 v58, vcc, s34, v52
	s_add_u32 s6, s23, s14
	s_nop 0
	v_addc_co_u32_e32 v59, vcc, 0, v53, vcc
	v_add_co_u32_e32 v60, vcc, s37, v52
	s_addc_u32 s13, s24, s15
	s_nop 0
	v_addc_co_u32_e32 v61, vcc, 0, v53, vcc
	v_add_co_u32_e32 v62, vcc, s38, v52
	s_lshl_b32 s11, s11, 18
	s_nop 0
	v_addc_co_u32_e32 v63, vcc, 0, v53, vcc
	v_add_co_u32_e32 v64, vcc, s39, v52
	s_add_u32 s6, s6, s11
	s_nop 0
	v_addc_co_u32_e32 v65, vcc, 0, v53, vcc
	v_add_co_u32_e32 v66, vcc, s40, v52
	s_addc_u32 s11, s13, 0
	s_nop 0
	v_addc_co_u32_e32 v67, vcc, 0, v53, vcc
	v_add_co_u32_e32 v68, vcc, s41, v52
	s_lshl_b32 s10, s10, 7
	s_nop 0
	v_addc_co_u32_e32 v69, vcc, 0, v53, vcc
	global_load_dword v11, v[54:55], off
	global_load_dword v13, v[56:57], off
	global_load_dword v15, v[58:59], off
	global_load_dword v17, v[60:61], off
	global_load_dword v19, v[62:63], off
	global_load_dword v21, v[64:65], off
	global_load_dword v23, v[66:67], off
	global_load_dword v25, v[68:69], off
	v_add_co_u32_e32 v54, vcc, s44, v52
	s_add_u32 s10, s6, s10
	s_nop 0
	v_addc_co_u32_e32 v55, vcc, 0, v53, vcc
	v_add_co_u32_e32 v56, vcc, s45, v52
	s_addc_u32 s11, s11, 0
	s_nop 0
	v_addc_co_u32_e32 v57, vcc, 0, v53, vcc
	v_add_co_u32_e32 v58, vcc, s46, v52
	s_nop 1
	v_addc_co_u32_e32 v59, vcc, 0, v53, vcc
	v_add_co_u32_e32 v60, vcc, s47, v52
	s_nop 1
	v_addc_co_u32_e32 v61, vcc, 0, v53, vcc
	v_add_co_u32_e32 v62, vcc, s48, v52
	s_nop 1
	v_addc_co_u32_e32 v63, vcc, 0, v53, vcc
	v_add_co_u32_e32 v64, vcc, s49, v52
	s_nop 1
	v_addc_co_u32_e32 v65, vcc, 0, v53, vcc
	v_add_co_u32_e32 v66, vcc, s51, v52
	s_nop 1
	v_addc_co_u32_e32 v67, vcc, 0, v53, vcc
	v_add_co_u32_e32 v68, vcc, s52, v52
	s_nop 1
	v_addc_co_u32_e32 v69, vcc, 0, v53, vcc
	global_load_dword v27, v[54:55], off
	global_load_dword v29, v[56:57], off
	global_load_dword v31, v[58:59], off
	global_load_dword v33, v[60:61], off
	global_load_dword v35, v[62:63], off
	global_load_dword v37, v[64:65], off
	global_load_dword v39, v[66:67], off
	global_load_dword v41, v[68:69], off
	v_add_co_u32_e32 v54, vcc, s53, v52
	s_nop 1
	v_addc_co_u32_e32 v55, vcc, 0, v53, vcc
	v_add_co_u32_e32 v56, vcc, s54, v52
	s_nop 1
	v_addc_co_u32_e32 v57, vcc, 0, v53, vcc
	v_add_co_u32_e32 v58, vcc, s55, v52
	s_nop 1
	v_addc_co_u32_e32 v59, vcc, 0, v53, vcc
	v_add_co_u32_e32 v60, vcc, s56, v52
	s_nop 1
	v_addc_co_u32_e32 v61, vcc, 0, v53, vcc
	v_add_co_u32_e32 v62, vcc, s57, v52
	s_nop 1
	v_addc_co_u32_e32 v63, vcc, 0, v53, vcc
	v_add_co_u32_e32 v64, vcc, s58, v52
	s_nop 1
	v_addc_co_u32_e32 v65, vcc, 0, v53, vcc
	v_add_co_u32_e32 v66, vcc, s59, v52
	s_nop 1
	v_addc_co_u32_e32 v67, vcc, 0, v53, vcc
	v_add_co_u32_e32 v68, vcc, s60, v52
	s_nop 1
	v_addc_co_u32_e32 v69, vcc, 0, v53, vcc
	global_load_dword v43, v[54:55], off
	global_load_dword v45, v[56:57], off
	global_load_dword v47, v[58:59], off
	global_load_dword v49, v[60:61], off
	global_load_dword v51, v[62:63], off
	global_load_dword v70, v[64:65], off
	global_load_dword v71, v[66:67], off
	global_load_dword v72, v[68:69], off
	v_add_co_u32_e32 v54, vcc, s61, v52
	s_nop 1
	v_addc_co_u32_e32 v55, vcc, 0, v53, vcc
	v_add_co_u32_e32 v56, vcc, s62, v52
	s_nop 1
	v_addc_co_u32_e32 v57, vcc, 0, v53, vcc
	v_add_co_u32_e32 v58, vcc, s63, v52
	s_nop 1
	v_addc_co_u32_e32 v59, vcc, 0, v53, vcc
	v_add_co_u32_e32 v60, vcc, s64, v52
	s_nop 1
	v_addc_co_u32_e32 v61, vcc, 0, v53, vcc
	v_add_co_u32_e32 v62, vcc, s65, v52
	s_nop 1
	v_addc_co_u32_e32 v63, vcc, 0, v53, vcc
	v_add_co_u32_e32 v64, vcc, s66, v52
	s_nop 1
	v_addc_co_u32_e32 v65, vcc, 0, v53, vcc
	v_add_co_u32_e32 v66, vcc, s67, v52
	s_nop 1
	v_addc_co_u32_e32 v67, vcc, 0, v53, vcc
	v_add_co_u32_e32 v68, vcc, s36, v52
	s_nop 1
	v_addc_co_u32_e32 v69, vcc, 0, v53, vcc
	global_load_dword v73, v[54:55], off
	global_load_dword v74, v[56:57], off
	global_load_dword v75, v[58:59], off
	global_load_dword v76, v[60:61], off
	global_load_dword v77, v[62:63], off
	global_load_dword v78, v[64:65], off
	global_load_dword v79, v[66:67], off
	global_load_dword v80, v[68:69], off
	v_add_co_u32_e32 v54, vcc, s68, v52
	s_nop 1
	v_addc_co_u32_e32 v55, vcc, 0, v53, vcc
	v_add_co_u32_e32 v56, vcc, s69, v52
	s_nop 1
	v_addc_co_u32_e32 v57, vcc, 0, v53, vcc
	v_add_co_u32_e32 v58, vcc, s70, v52
	s_nop 1
	v_addc_co_u32_e32 v59, vcc, 0, v53, vcc
	v_add_co_u32_e32 v60, vcc, s71, v52
	s_nop 1
	v_addc_co_u32_e32 v61, vcc, 0, v53, vcc
	v_add_co_u32_e32 v62, vcc, s72, v52
	s_nop 1
	v_addc_co_u32_e32 v63, vcc, 0, v53, vcc
	v_add_co_u32_e32 v64, vcc, s73, v52
	s_nop 1
	v_addc_co_u32_e32 v65, vcc, 0, v53, vcc
	v_add_co_u32_e32 v66, vcc, s74, v52
	s_nop 1
	v_addc_co_u32_e32 v67, vcc, 0, v53, vcc
	v_add_co_u32_e32 v68, vcc, s75, v52
	s_nop 1
	v_addc_co_u32_e32 v69, vcc, 0, v53, vcc
	global_load_dword v81, v[54:55], off
	global_load_dword v82, v[56:57], off
	global_load_dword v83, v[58:59], off
	global_load_dword v84, v[60:61], off
	global_load_dword v85, v[62:63], off
	global_load_dword v86, v[64:65], off
	global_load_dword v87, v[66:67], off
	global_load_dword v88, v[68:69], off
	v_add_co_u32_e32 v54, vcc, s80, v52
	s_nop 1
	v_addc_co_u32_e32 v55, vcc, 0, v53, vcc
	v_add_co_u32_e32 v56, vcc, s81, v52
	s_nop 1
	v_addc_co_u32_e32 v57, vcc, 0, v53, vcc
	v_add_co_u32_e32 v58, vcc, s82, v52
	s_nop 1
	v_addc_co_u32_e32 v59, vcc, 0, v53, vcc
	v_add_co_u32_e32 v60, vcc, s83, v52
	s_nop 1
	v_addc_co_u32_e32 v61, vcc, 0, v53, vcc
	v_add_co_u32_e32 v62, vcc, s84, v52
	s_nop 1
	v_addc_co_u32_e32 v63, vcc, 0, v53, vcc
	v_add_co_u32_e32 v64, vcc, s85, v52
	s_nop 1
	v_addc_co_u32_e32 v65, vcc, 0, v53, vcc
	v_add_co_u32_e32 v66, vcc, s86, v52
	s_nop 1
	v_addc_co_u32_e32 v67, vcc, 0, v53, vcc
	v_add_co_u32_e32 v68, vcc, s87, v52
	s_nop 1
	v_addc_co_u32_e32 v69, vcc, 0, v53, vcc
	global_load_dword v89, v[54:55], off
	global_load_dword v90, v[56:57], off
	global_load_dword v91, v[58:59], off
	global_load_dword v92, v[60:61], off
	global_load_dword v93, v[62:63], off
	global_load_dword v94, v[64:65], off
	global_load_dword v95, v[66:67], off
	global_load_dword v96, v[68:69], off
	v_add_co_u32_e32 v54, vcc, s88, v52
	s_nop 1
	v_addc_co_u32_e32 v55, vcc, 0, v53, vcc
	v_add_co_u32_e32 v56, vcc, s89, v52
	s_nop 1
	v_addc_co_u32_e32 v57, vcc, 0, v53, vcc
	v_add_co_u32_e32 v58, vcc, s90, v52
	s_nop 1
	v_addc_co_u32_e32 v59, vcc, 0, v53, vcc
	v_add_co_u32_e32 v60, vcc, s91, v52
	s_nop 1
	v_addc_co_u32_e32 v61, vcc, 0, v53, vcc
	v_add_co_u32_e32 v62, vcc, s92, v52
	s_nop 1
	v_addc_co_u32_e32 v63, vcc, 0, v53, vcc
	v_add_co_u32_e32 v64, vcc, s93, v52
	s_nop 1
	v_addc_co_u32_e32 v65, vcc, 0, v53, vcc
	v_add_co_u32_e32 v66, vcc, s94, v52
	s_nop 1
	v_addc_co_u32_e32 v67, vcc, 0, v53, vcc
	v_add_co_u32_e32 v68, vcc, s95, v52
	s_nop 1
	v_addc_co_u32_e32 v69, vcc, 0, v53, vcc
	global_load_dword v97, v[54:55], off
	global_load_dword v98, v[56:57], off
	global_load_dword v99, v[58:59], off
	global_load_dword v100, v[60:61], off
	global_load_dword v101, v[62:63], off
	global_load_dword v102, v[64:65], off
	s_nop 0
	global_load_dword v66, v[66:67], off
	s_nop 0
	global_load_dword v67, v[68:69], off
	v_add_co_u32_e32 v54, vcc, s96, v52
	s_nop 1
	v_addc_co_u32_e32 v55, vcc, 0, v53, vcc
	v_add_co_u32_e32 v56, vcc, s97, v52
	s_nop 1
	v_addc_co_u32_e32 v57, vcc, 0, v53, vcc
	v_add_co_u32_e32 v58, vcc, s50, v52
	s_nop 1
	v_addc_co_u32_e32 v59, vcc, 0, v53, vcc
	v_add_co_u32_e32 v60, vcc, s17, v52
	s_nop 1
	v_addc_co_u32_e32 v61, vcc, 0, v53, vcc
	v_add_co_u32_e32 v62, vcc, s18, v52
	s_nop 1
	v_addc_co_u32_e32 v63, vcc, 0, v53, vcc
	v_add_co_u32_e32 v64, vcc, s19, v52
	s_nop 1
	v_addc_co_u32_e32 v65, vcc, 0, v53, vcc
	v_add_co_u32_e32 v52, vcc, s20, v52
	s_nop 1
	v_addc_co_u32_e32 v53, vcc, 0, v53, vcc
	global_load_dword v68, v[54:55], off
	s_nop 0
	global_load_dword v56, v[56:57], off
	s_nop 0
	global_load_dword v57, v[58:59], off
	s_nop 0
	global_load_dword v58, v[60:61], off
	global_load_dword v59, v[62:63], off
	s_nop 0
	global_load_dword v60, v[64:65], off
	global_load_dword v61, v[52:53], off
	s_waitcnt vmcnt(62)
	v_cvt_pk_bf16_f32 v52, v9, v11
	s_waitcnt vmcnt(60)
	v_cvt_pk_bf16_f32 v53, v13, v15
	s_waitcnt vmcnt(58)
	v_cvt_pk_bf16_f32 v54, v17, v19
	s_waitcnt vmcnt(56)
	v_cvt_pk_bf16_f32 v55, v21, v23
	ds_write_b128 v5, v[52:55]
	s_waitcnt vmcnt(54)
	v_cvt_pk_bf16_f32 v52, v25, v27
	s_waitcnt vmcnt(52)
	v_cvt_pk_bf16_f32 v53, v29, v31
	s_waitcnt vmcnt(50)
	v_cvt_pk_bf16_f32 v54, v33, v35
	s_waitcnt vmcnt(48)
	v_cvt_pk_bf16_f32 v55, v37, v39
	ds_write_b128 v5, v[52:55] offset:16
	s_waitcnt vmcnt(46)
	v_cvt_pk_bf16_f32 v52, v41, v43
	s_waitcnt vmcnt(44)
	v_cvt_pk_bf16_f32 v53, v45, v47
	s_waitcnt vmcnt(42)
	v_cvt_pk_bf16_f32 v54, v49, v51
	s_waitcnt vmcnt(40)
	v_cvt_pk_bf16_f32 v55, v70, v71
	ds_write_b128 v5, v[52:55] offset:32
	s_waitcnt vmcnt(38)
	v_cvt_pk_bf16_f32 v52, v72, v73
	s_waitcnt vmcnt(36)
	v_cvt_pk_bf16_f32 v53, v74, v75
	s_waitcnt vmcnt(34)
	v_cvt_pk_bf16_f32 v54, v76, v77
	s_waitcnt vmcnt(32)
	v_cvt_pk_bf16_f32 v55, v78, v79
	ds_write_b128 v5, v[52:55] offset:48
	s_waitcnt vmcnt(30)
	v_cvt_pk_bf16_f32 v52, v80, v81
	s_waitcnt vmcnt(28)
	v_cvt_pk_bf16_f32 v53, v82, v83
	s_waitcnt vmcnt(26)
	v_cvt_pk_bf16_f32 v54, v84, v85
	s_waitcnt vmcnt(24)
	v_cvt_pk_bf16_f32 v55, v86, v87
	ds_write_b128 v5, v[52:55] offset:64
	s_waitcnt vmcnt(22)
	v_cvt_pk_bf16_f32 v52, v88, v89
	s_waitcnt vmcnt(20)
	v_cvt_pk_bf16_f32 v53, v90, v91
	s_waitcnt vmcnt(18)
	v_cvt_pk_bf16_f32 v54, v92, v93
	s_waitcnt vmcnt(16)
	v_cvt_pk_bf16_f32 v55, v94, v95
	ds_write_b128 v5, v[52:55] offset:80
	v_mov_b32_e32 v51, v1
	s_waitcnt vmcnt(14)
	v_cvt_pk_bf16_f32 v52, v96, v97
	s_waitcnt vmcnt(12)
	v_cvt_pk_bf16_f32 v53, v98, v99
	s_waitcnt vmcnt(10)
	v_cvt_pk_bf16_f32 v54, v100, v101
	s_waitcnt vmcnt(8)
	v_cvt_pk_bf16_f32 v55, v102, v66
	ds_write_b128 v5, v[52:55] offset:96
	s_waitcnt vmcnt(6)
	v_cvt_pk_bf16_f32 v52, v67, v68
	s_waitcnt vmcnt(4)
	v_cvt_pk_bf16_f32 v53, v56, v57
	v_lshlrev_b32_e32 v56, 1, v2
	s_waitcnt vmcnt(2)
	v_cvt_pk_bf16_f32 v54, v58, v59
	v_mov_b32_e32 v57, v1
	s_waitcnt vmcnt(0)
	v_cvt_pk_bf16_f32 v55, v60, v61
	ds_write_b128 v5, v[52:55] offset:112
	s_waitcnt lgkmcnt(0)
	ds_read_b128 v[52:55], v7
	v_lshl_add_u64 v[60:61], s[10:11], 0, v[50:51]
	v_lshl_add_u64 v[62:63], v[60:61], 0, v[56:57]
	ds_read_b128 v[56:59], v7 offset:1152
	s_waitcnt lgkmcnt(1)
	global_store_dwordx4 v[62:63], v[52:55], off sc0 sc1
	s_nop 1
	v_lshlrev_b32_e32 v52, 1, v4
	v_mov_b32_e32 v53, v1
	v_lshl_add_u64 v[52:53], v[60:61], 0, v[52:53]
	s_waitcnt lgkmcnt(0)
	global_store_dwordx4 v[52:53], v[56:59], off sc0 sc1
	ds_read_b128 v[52:55], v7 offset:2304
	s_nop 0
	v_lshlrev_b32_e32 v56, 1, v6
	v_mov_b32_e32 v57, v1
	v_lshl_add_u64 v[62:63], v[60:61], 0, v[56:57]
	ds_read_b128 v[56:59], v7 offset:3456
	s_waitcnt lgkmcnt(1)
	global_store_dwordx4 v[62:63], v[52:55], off sc0 sc1
	s_nop 1
	v_lshlrev_b32_e32 v52, 1, v8
	v_mov_b32_e32 v53, v1
	v_lshl_add_u64 v[52:53], v[60:61], 0, v[52:53]
	s_waitcnt lgkmcnt(0)
	global_store_dwordx4 v[52:53], v[56:59], off sc0 sc1
	ds_read_b128 v[52:55], v7 offset:4608
	s_nop 0
	v_lshlrev_b32_e32 v56, 1, v10
	v_mov_b32_e32 v57, v1
	v_lshl_add_u64 v[62:63], v[60:61], 0, v[56:57]
	ds_read_b128 v[56:59], v7 offset:5760
	s_waitcnt lgkmcnt(1)
	global_store_dwordx4 v[62:63], v[52:55], off sc0 sc1
	s_nop 1
	v_lshlrev_b32_e32 v52, 1, v12
	v_mov_b32_e32 v53, v1
	v_lshl_add_u64 v[52:53], v[60:61], 0, v[52:53]
	s_waitcnt lgkmcnt(0)
	global_store_dwordx4 v[52:53], v[56:59], off sc0 sc1
	ds_read_b128 v[52:55], v7 offset:6912
	s_nop 0
	v_lshlrev_b32_e32 v56, 1, v14
	v_mov_b32_e32 v57, v1
	v_lshl_add_u64 v[62:63], v[60:61], 0, v[56:57]
	ds_read_b128 v[56:59], v7 offset:8064
	s_waitcnt lgkmcnt(1)
	global_store_dwordx4 v[62:63], v[52:55], off sc0 sc1
	s_nop 1
	v_lshlrev_b32_e32 v52, 1, v16
	v_mov_b32_e32 v53, v1
	v_lshl_add_u64 v[52:53], v[60:61], 0, v[52:53]
	s_waitcnt lgkmcnt(0)
	global_store_dwordx4 v[52:53], v[56:59], off sc0 sc1
	s_waitcnt lgkmcnt(0)

.LBB0_88:
	s_andn2_b64 vcc, exec, s[10:11]
	s_cbranch_vccnz .LBB0_90
	s_load_dwordx2 s[14:15], s[0:1], 0x80
	s_add_i32 s10, s12, 0xffffab00
	s_lshr_b32 s6, s10, 10
	s_bfe_u32 s10, s10, 0x50005
	s_and_b32 s11, s12, 31
	s_lshl_b64 vcc, s[6:7], 24
	s_waitcnt lgkmcnt(0)
	s_add_u32 s13, s14, vcc_lo
	s_addc_u32 s14, s15, vcc_hi
	s_lshl_b32 s15, s10, 19
	s_add_u32 s13, s13, s15
	s_addc_u32 s15, s14, 0
	s_lshl_b32 s14, s11, 8
	s_add_u32 s14, s13, s14
	s_addc_u32 s15, s15, 0
	v_lshl_add_u64 v[52:53], s[14:15], 0, v[0:1]
	v_add_co_u32_e32 v54, vcc, s28, v52
	global_load_dword v9, v0, s[14:15]
	s_nop 0
	v_addc_co_u32_e32 v55, vcc, 0, v53, vcc
	v_add_co_u32_e32 v56, vcc, s30, v52
	s_lshl_b64 s[14:15], s[6:7], 23
	s_nop 0
	v_addc_co_u32_e32 v57, vcc, 0, v53, vcc
	v_add_co_u32_e32 v58, vcc, s34, v52
	s_add_u32 s6, s25, s14
	s_nop 0
	v_addc_co_u32_e32 v59, vcc, 0, v53, vcc
	v_add_co_u32_e32 v60, vcc, s37, v52
	s_addc_u32 s13, s26, s15
	s_nop 0
	v_addc_co_u32_e32 v61, vcc, 0, v53, vcc
	v_add_co_u32_e32 v62, vcc, s38, v52
	s_lshl_b32 s11, s11, 18
	s_nop 0
	v_addc_co_u32_e32 v63, vcc, 0, v53, vcc
	v_add_co_u32_e32 v64, vcc, s39, v52
	s_add_u32 s6, s6, s11
	s_nop 0
	v_addc_co_u32_e32 v65, vcc, 0, v53, vcc
	v_add_co_u32_e32 v66, vcc, s40, v52
	s_addc_u32 s11, s13, 0
	s_nop 0
	v_addc_co_u32_e32 v67, vcc, 0, v53, vcc
	v_add_co_u32_e32 v68, vcc, s41, v52
	s_lshl_b32 s10, s10, 7
	s_nop 0
	v_addc_co_u32_e32 v69, vcc, 0, v53, vcc
	global_load_dword v11, v[54:55], off
	global_load_dword v13, v[56:57], off
	global_load_dword v15, v[58:59], off
	global_load_dword v17, v[60:61], off
	global_load_dword v19, v[62:63], off
	global_load_dword v21, v[64:65], off
	global_load_dword v23, v[66:67], off
	global_load_dword v25, v[68:69], off
	v_add_co_u32_e32 v54, vcc, s44, v52
	s_add_u32 s10, s6, s10
	s_nop 0
	v_addc_co_u32_e32 v55, vcc, 0, v53, vcc
	v_add_co_u32_e32 v56, vcc, s45, v52
	s_addc_u32 s11, s11, 0
	s_nop 0
	v_addc_co_u32_e32 v57, vcc, 0, v53, vcc
	v_add_co_u32_e32 v58, vcc, s46, v52
	s_nop 1
	v_addc_co_u32_e32 v59, vcc, 0, v53, vcc
	v_add_co_u32_e32 v60, vcc, s47, v52
	s_nop 1
	v_addc_co_u32_e32 v61, vcc, 0, v53, vcc
	v_add_co_u32_e32 v62, vcc, s48, v52
	s_nop 1
	v_addc_co_u32_e32 v63, vcc, 0, v53, vcc
	v_add_co_u32_e32 v64, vcc, s49, v52
	s_nop 1
	v_addc_co_u32_e32 v65, vcc, 0, v53, vcc
	v_add_co_u32_e32 v66, vcc, s51, v52
	s_nop 1
	v_addc_co_u32_e32 v67, vcc, 0, v53, vcc
	v_add_co_u32_e32 v68, vcc, s52, v52
	s_nop 1
	v_addc_co_u32_e32 v69, vcc, 0, v53, vcc
	global_load_dword v27, v[54:55], off
	global_load_dword v29, v[56:57], off
	global_load_dword v31, v[58:59], off
	global_load_dword v33, v[60:61], off
	global_load_dword v35, v[62:63], off
	global_load_dword v37, v[64:65], off
	global_load_dword v39, v[66:67], off
	global_load_dword v41, v[68:69], off
	v_add_co_u32_e32 v54, vcc, s53, v52
	s_nop 1
	v_addc_co_u32_e32 v55, vcc, 0, v53, vcc
	v_add_co_u32_e32 v56, vcc, s54, v52
	s_nop 1
	v_addc_co_u32_e32 v57, vcc, 0, v53, vcc
	v_add_co_u32_e32 v58, vcc, s55, v52
	s_nop 1
	v_addc_co_u32_e32 v59, vcc, 0, v53, vcc
	v_add_co_u32_e32 v60, vcc, s56, v52
	s_nop 1
	v_addc_co_u32_e32 v61, vcc, 0, v53, vcc
	v_add_co_u32_e32 v62, vcc, s57, v52
	s_nop 1
	v_addc_co_u32_e32 v63, vcc, 0, v53, vcc
	v_add_co_u32_e32 v64, vcc, s58, v52
	s_nop 1
	v_addc_co_u32_e32 v65, vcc, 0, v53, vcc
	v_add_co_u32_e32 v66, vcc, s59, v52
	s_nop 1
	v_addc_co_u32_e32 v67, vcc, 0, v53, vcc
	v_add_co_u32_e32 v68, vcc, s60, v52
	s_nop 1
	v_addc_co_u32_e32 v69, vcc, 0, v53, vcc
	global_load_dword v43, v[54:55], off
	global_load_dword v45, v[56:57], off
	global_load_dword v47, v[58:59], off
	global_load_dword v49, v[60:61], off
	global_load_dword v51, v[62:63], off
	global_load_dword v70, v[64:65], off
	global_load_dword v71, v[66:67], off
	global_load_dword v72, v[68:69], off
	v_add_co_u32_e32 v54, vcc, s61, v52
	s_nop 1
	v_addc_co_u32_e32 v55, vcc, 0, v53, vcc
	v_add_co_u32_e32 v56, vcc, s62, v52
	s_nop 1
	v_addc_co_u32_e32 v57, vcc, 0, v53, vcc
	v_add_co_u32_e32 v58, vcc, s63, v52
	s_nop 1
	v_addc_co_u32_e32 v59, vcc, 0, v53, vcc
	v_add_co_u32_e32 v60, vcc, s64, v52
	s_nop 1
	v_addc_co_u32_e32 v61, vcc, 0, v53, vcc
	v_add_co_u32_e32 v62, vcc, s65, v52
	s_nop 1
	v_addc_co_u32_e32 v63, vcc, 0, v53, vcc
	v_add_co_u32_e32 v64, vcc, s66, v52
	s_nop 1
	v_addc_co_u32_e32 v65, vcc, 0, v53, vcc
	v_add_co_u32_e32 v66, vcc, s67, v52
	s_nop 1
	v_addc_co_u32_e32 v67, vcc, 0, v53, vcc
	v_add_co_u32_e32 v68, vcc, s36, v52
	s_nop 1
	v_addc_co_u32_e32 v69, vcc, 0, v53, vcc
	global_load_dword v73, v[54:55], off
	global_load_dword v74, v[56:57], off
	global_load_dword v75, v[58:59], off
	global_load_dword v76, v[60:61], off
	global_load_dword v77, v[62:63], off
	global_load_dword v78, v[64:65], off
	global_load_dword v79, v[66:67], off
	global_load_dword v80, v[68:69], off
	v_add_co_u32_e32 v54, vcc, s68, v52
	s_nop 1
	v_addc_co_u32_e32 v55, vcc, 0, v53, vcc
	v_add_co_u32_e32 v56, vcc, s69, v52
	s_nop 1
	v_addc_co_u32_e32 v57, vcc, 0, v53, vcc
	v_add_co_u32_e32 v58, vcc, s70, v52
	s_nop 1
	v_addc_co_u32_e32 v59, vcc, 0, v53, vcc
	v_add_co_u32_e32 v60, vcc, s71, v52
	s_nop 1
	v_addc_co_u32_e32 v61, vcc, 0, v53, vcc
	v_add_co_u32_e32 v62, vcc, s72, v52
	s_nop 1
	v_addc_co_u32_e32 v63, vcc, 0, v53, vcc
	v_add_co_u32_e32 v64, vcc, s73, v52
	s_nop 1
	v_addc_co_u32_e32 v65, vcc, 0, v53, vcc
	v_add_co_u32_e32 v66, vcc, s74, v52
	s_nop 1
	v_addc_co_u32_e32 v67, vcc, 0, v53, vcc
	v_add_co_u32_e32 v68, vcc, s75, v52
	s_nop 1
	v_addc_co_u32_e32 v69, vcc, 0, v53, vcc
	global_load_dword v81, v[54:55], off
	global_load_dword v82, v[56:57], off
	global_load_dword v83, v[58:59], off
	global_load_dword v84, v[60:61], off
	global_load_dword v85, v[62:63], off
	global_load_dword v86, v[64:65], off
	global_load_dword v87, v[66:67], off
	global_load_dword v88, v[68:69], off
	v_add_co_u32_e32 v54, vcc, s80, v52
	s_nop 1
	v_addc_co_u32_e32 v55, vcc, 0, v53, vcc
	v_add_co_u32_e32 v56, vcc, s81, v52
	s_nop 1
	v_addc_co_u32_e32 v57, vcc, 0, v53, vcc
	v_add_co_u32_e32 v58, vcc, s82, v52
	s_nop 1
	v_addc_co_u32_e32 v59, vcc, 0, v53, vcc
	v_add_co_u32_e32 v60, vcc, s83, v52
	s_nop 1
	v_addc_co_u32_e32 v61, vcc, 0, v53, vcc
	v_add_co_u32_e32 v62, vcc, s84, v52
	s_nop 1
	v_addc_co_u32_e32 v63, vcc, 0, v53, vcc
	v_add_co_u32_e32 v64, vcc, s85, v52
	s_nop 1
	v_addc_co_u32_e32 v65, vcc, 0, v53, vcc
	v_add_co_u32_e32 v66, vcc, s86, v52
	s_nop 1
	v_addc_co_u32_e32 v67, vcc, 0, v53, vcc
	v_add_co_u32_e32 v68, vcc, s87, v52
	s_nop 1
	v_addc_co_u32_e32 v69, vcc, 0, v53, vcc
	global_load_dword v89, v[54:55], off
	global_load_dword v90, v[56:57], off
	global_load_dword v91, v[58:59], off
	global_load_dword v92, v[60:61], off
	global_load_dword v93, v[62:63], off
	global_load_dword v94, v[64:65], off
	global_load_dword v95, v[66:67], off
	global_load_dword v96, v[68:69], off
	v_add_co_u32_e32 v54, vcc, s88, v52
	s_nop 1
	v_addc_co_u32_e32 v55, vcc, 0, v53, vcc
	v_add_co_u32_e32 v56, vcc, s89, v52
	s_nop 1
	v_addc_co_u32_e32 v57, vcc, 0, v53, vcc
	v_add_co_u32_e32 v58, vcc, s90, v52
	s_nop 1
	v_addc_co_u32_e32 v59, vcc, 0, v53, vcc
	v_add_co_u32_e32 v60, vcc, s91, v52
	s_nop 1
	v_addc_co_u32_e32 v61, vcc, 0, v53, vcc
	v_add_co_u32_e32 v62, vcc, s92, v52
	s_nop 1
	v_addc_co_u32_e32 v63, vcc, 0, v53, vcc
	v_add_co_u32_e32 v64, vcc, s93, v52
	s_nop 1
	v_addc_co_u32_e32 v65, vcc, 0, v53, vcc
	v_add_co_u32_e32 v66, vcc, s94, v52
	s_nop 1
	v_addc_co_u32_e32 v67, vcc, 0, v53, vcc
	v_add_co_u32_e32 v68, vcc, s95, v52
	s_nop 1
	v_addc_co_u32_e32 v69, vcc, 0, v53, vcc
	global_load_dword v97, v[54:55], off
	global_load_dword v98, v[56:57], off
	global_load_dword v99, v[58:59], off
	global_load_dword v100, v[60:61], off
	global_load_dword v101, v[62:63], off
	global_load_dword v102, v[64:65], off
	s_nop 0
	global_load_dword v66, v[66:67], off
	s_nop 0
	global_load_dword v67, v[68:69], off
	v_add_co_u32_e32 v54, vcc, s96, v52
	s_nop 1
	v_addc_co_u32_e32 v55, vcc, 0, v53, vcc
	v_add_co_u32_e32 v56, vcc, s97, v52
	s_nop 1
	v_addc_co_u32_e32 v57, vcc, 0, v53, vcc
	v_add_co_u32_e32 v58, vcc, s50, v52
	s_nop 1
	v_addc_co_u32_e32 v59, vcc, 0, v53, vcc
	v_add_co_u32_e32 v60, vcc, s17, v52
	s_nop 1
	v_addc_co_u32_e32 v61, vcc, 0, v53, vcc
	v_add_co_u32_e32 v62, vcc, s18, v52
	s_nop 1
	v_addc_co_u32_e32 v63, vcc, 0, v53, vcc
	v_add_co_u32_e32 v64, vcc, s19, v52
	s_nop 1
	v_addc_co_u32_e32 v65, vcc, 0, v53, vcc
	v_add_co_u32_e32 v52, vcc, s20, v52
	s_nop 1
	v_addc_co_u32_e32 v53, vcc, 0, v53, vcc
	global_load_dword v68, v[54:55], off
	s_nop 0
	global_load_dword v56, v[56:57], off
	s_nop 0
	global_load_dword v57, v[58:59], off
	s_nop 0
	global_load_dword v58, v[60:61], off
	global_load_dword v59, v[62:63], off
	s_nop 0
	global_load_dword v60, v[64:65], off
	global_load_dword v61, v[52:53], off
	s_waitcnt vmcnt(62)
	v_cvt_pk_bf16_f32 v52, v9, v11
	s_waitcnt vmcnt(60)
	v_cvt_pk_bf16_f32 v53, v13, v15
	s_waitcnt vmcnt(58)
	v_cvt_pk_bf16_f32 v54, v17, v19
	s_waitcnt vmcnt(56)
	v_cvt_pk_bf16_f32 v55, v21, v23
	ds_write_b128 v5, v[52:55]
	s_waitcnt vmcnt(54)
	v_cvt_pk_bf16_f32 v52, v25, v27
	s_waitcnt vmcnt(52)
	v_cvt_pk_bf16_f32 v53, v29, v31
	s_waitcnt vmcnt(50)
	v_cvt_pk_bf16_f32 v54, v33, v35
	s_waitcnt vmcnt(48)
	v_cvt_pk_bf16_f32 v55, v37, v39
	ds_write_b128 v5, v[52:55] offset:16
	s_waitcnt vmcnt(46)
	v_cvt_pk_bf16_f32 v52, v41, v43
	s_waitcnt vmcnt(44)
	v_cvt_pk_bf16_f32 v53, v45, v47
	s_waitcnt vmcnt(42)
	v_cvt_pk_bf16_f32 v54, v49, v51
	s_waitcnt vmcnt(40)
	v_cvt_pk_bf16_f32 v55, v70, v71
	ds_write_b128 v5, v[52:55] offset:32
	s_waitcnt vmcnt(38)
	v_cvt_pk_bf16_f32 v52, v72, v73
	s_waitcnt vmcnt(36)
	v_cvt_pk_bf16_f32 v53, v74, v75
	s_waitcnt vmcnt(34)
	v_cvt_pk_bf16_f32 v54, v76, v77
	s_waitcnt vmcnt(32)
	v_cvt_pk_bf16_f32 v55, v78, v79
	ds_write_b128 v5, v[52:55] offset:48
	s_waitcnt vmcnt(30)
	v_cvt_pk_bf16_f32 v52, v80, v81
	s_waitcnt vmcnt(28)
	v_cvt_pk_bf16_f32 v53, v82, v83
	s_waitcnt vmcnt(26)
	v_cvt_pk_bf16_f32 v54, v84, v85
	s_waitcnt vmcnt(24)
	v_cvt_pk_bf16_f32 v55, v86, v87
	ds_write_b128 v5, v[52:55] offset:64
	s_waitcnt vmcnt(22)
	v_cvt_pk_bf16_f32 v52, v88, v89
	s_waitcnt vmcnt(20)
	v_cvt_pk_bf16_f32 v53, v90, v91
	s_waitcnt vmcnt(18)
	v_cvt_pk_bf16_f32 v54, v92, v93
	s_waitcnt vmcnt(16)
	v_cvt_pk_bf16_f32 v55, v94, v95
	ds_write_b128 v5, v[52:55] offset:80
	v_mov_b32_e32 v51, v1
	s_waitcnt vmcnt(14)
	v_cvt_pk_bf16_f32 v52, v96, v97
	s_waitcnt vmcnt(12)
	v_cvt_pk_bf16_f32 v53, v98, v99
	s_waitcnt vmcnt(10)
	v_cvt_pk_bf16_f32 v54, v100, v101
	s_waitcnt vmcnt(8)
	v_cvt_pk_bf16_f32 v55, v102, v66
	ds_write_b128 v5, v[52:55] offset:96
	s_waitcnt vmcnt(6)
	v_cvt_pk_bf16_f32 v52, v67, v68
	s_waitcnt vmcnt(4)
	v_cvt_pk_bf16_f32 v53, v56, v57
	v_lshlrev_b32_e32 v56, 1, v2
	s_waitcnt vmcnt(2)
	v_cvt_pk_bf16_f32 v54, v58, v59
	v_mov_b32_e32 v57, v1
	s_waitcnt vmcnt(0)
	v_cvt_pk_bf16_f32 v55, v60, v61
	ds_write_b128 v5, v[52:55] offset:112
	s_waitcnt lgkmcnt(0)
	ds_read_b128 v[52:55], v7
	v_lshl_add_u64 v[60:61], s[10:11], 0, v[50:51]
	v_lshl_add_u64 v[62:63], v[60:61], 0, v[56:57]
	ds_read_b128 v[56:59], v7 offset:1152
	s_waitcnt lgkmcnt(1)
	global_store_dwordx4 v[62:63], v[52:55], off sc0 sc1
	s_nop 1
	v_lshlrev_b32_e32 v52, 1, v4
	v_mov_b32_e32 v53, v1
	v_lshl_add_u64 v[52:53], v[60:61], 0, v[52:53]
	s_waitcnt lgkmcnt(0)
	global_store_dwordx4 v[52:53], v[56:59], off sc0 sc1
	ds_read_b128 v[52:55], v7 offset:2304
	s_nop 0
	v_lshlrev_b32_e32 v56, 1, v6
	v_mov_b32_e32 v57, v1
	v_lshl_add_u64 v[62:63], v[60:61], 0, v[56:57]
	ds_read_b128 v[56:59], v7 offset:3456
	s_waitcnt lgkmcnt(1)
	global_store_dwordx4 v[62:63], v[52:55], off sc0 sc1
	s_nop 1
	v_lshlrev_b32_e32 v52, 1, v8
	v_mov_b32_e32 v53, v1
	v_lshl_add_u64 v[52:53], v[60:61], 0, v[52:53]
	s_waitcnt lgkmcnt(0)
	global_store_dwordx4 v[52:53], v[56:59], off sc0 sc1
	ds_read_b128 v[52:55], v7 offset:4608
	s_nop 0
	v_lshlrev_b32_e32 v56, 1, v10
	v_mov_b32_e32 v57, v1
	v_lshl_add_u64 v[62:63], v[60:61], 0, v[56:57]
	ds_read_b128 v[56:59], v7 offset:5760
	s_waitcnt lgkmcnt(1)
	global_store_dwordx4 v[62:63], v[52:55], off sc0 sc1
	s_nop 1
	v_lshlrev_b32_e32 v52, 1, v12
	v_mov_b32_e32 v53, v1
	v_lshl_add_u64 v[52:53], v[60:61], 0, v[52:53]
	s_waitcnt lgkmcnt(0)
	global_store_dwordx4 v[52:53], v[56:59], off sc0 sc1
	ds_read_b128 v[52:55], v7 offset:6912
	s_nop 0
	v_lshlrev_b32_e32 v56, 1, v14
	v_mov_b32_e32 v57, v1
	v_lshl_add_u64 v[62:63], v[60:61], 0, v[56:57]
	ds_read_b128 v[56:59], v7 offset:8064
	s_waitcnt lgkmcnt(1)
	global_store_dwordx4 v[62:63], v[52:55], off sc0 sc1
	s_nop 1
	v_lshlrev_b32_e32 v52, 1, v16
	v_mov_b32_e32 v53, v1
	v_lshl_add_u64 v[52:53], v[60:61], 0, v[52:53]
	s_waitcnt lgkmcnt(0)
	global_store_dwordx4 v[52:53], v[56:59], off sc0 sc1
	s_waitcnt lgkmcnt(0)
